# P1 compose items: the 32 Wc/Ws values of k-step i+1 requested while step i computes (step 0 before the loop), copied into the working registers at the step top
# speedup vs baseline: 1.0247x; 1.0042x over previous
; DEVI void compose_item(const P& p, int it, float* sm) {
;     const int tid = threadIdx.x;
;     const int g = it >> 5, j0 = (it & 31) * 32;
;     __syncthreads();
; #pragma unroll
;     for (int i = 0; i < 4; ++i) {
;         const int row = (tid >> 5) + 8 * i, c4 = (tid & 31) * 4;
;         *(float4*)(sm + row * 128 + c4) = *(const float4*)(p.w_in0 + (size_t)(j0 + row) * 4096 + 2048 + 128 * g + c4);
;     }
;     __syncthreads();
;     const int e = tid & 127, half = tid >> 7;
;     const float* wc = (const float*)(p.ws + OFF_WCS) + (size_t)g * 16384 + e;
;     const float* wsn = wc + 131072;
;     float ap[16], aq[16];
; #pragma unroll
;     for (int jj = 0; jj < 16; ++jj) { ap[jj] = 0.f; aq[jj] = 0.f; }
; #pragma unroll 1
;     for (int d0 = 0; d0 < 128; d0 += 16) {
;         float cw[16], sw[16];
; #pragma unroll
;         for (int u = 0; u < 16; ++u) { cw[u] = wc[(d0 + u) * 128]; sw[u] = wsn[(d0 + u) * 128]; }
.LBB0_161:
	s_lshl_b32 s0, s61, 5
	s_ashr_i32 s6, s61, 5
	s_and_b32 s8, s0, 0x3e0
	s_lshl_b32 s0, s6, 7
	v_or_b32_e32 v0, s8, v117
	v_readlane_b32 s68, v230, 0
	s_ashr_i32 s1, s0, 31
	v_lshlrev_b32_e32 v44, 12, v0
	v_readlane_b32 s69, v230, 1
	s_lshl_b64 s[10:11], s[0:1], 2
	v_mov_b32_e32 v79, v45
	v_lshl_add_u64 v[0:1], v[44:45], 2, s[68:69]
	v_lshl_add_u64 v[0:1], v[0:1], 0, s[10:11]
	v_add_lshl_u32 v44, s8, v121, 12
	v_lshl_add_u64 v[0:1], v[0:1], 0, v[78:79]
	v_lshl_add_u64 v[2:3], v[44:45], 2, s[68:69]
	v_add_co_u32_e32 v0, vcc, s60, v0
	v_lshl_add_u64 v[2:3], v[2:3], 0, s[10:11]
	v_add_lshl_u32 v44, s8, v125, 12
	v_addc_co_u32_e32 v1, vcc, 0, v1, vcc
	v_lshl_add_u64 v[2:3], v[2:3], 0, v[78:79]
	v_lshl_add_u64 v[8:9], v[44:45], 2, s[68:69]
	v_add_co_u32_e32 v4, vcc, s60, v2
	v_lshl_add_u64 v[8:9], v[8:9], 0, s[10:11]
	v_add_lshl_u32 v44, s8, v129, 12
	v_addc_co_u32_e32 v5, vcc, 0, v3, vcc
	v_lshl_add_u64 v[8:9], v[8:9], 0, v[78:79]
	v_lshl_add_u64 v[10:11], v[44:45], 2, s[68:69]
	v_add_co_u32_e32 v8, vcc, s60, v8
	v_lshl_add_u64 v[10:11], v[10:11], 0, s[10:11]
	s_nop 0
	v_addc_co_u32_e32 v9, vcc, 0, v9, vcc
	v_lshl_add_u64 v[10:11], v[10:11], 0, v[78:79]
	v_add_co_u32_e32 v12, vcc, 0x2000, v10
	s_nop 1
	v_addc_co_u32_e32 v13, vcc, 0, v11, vcc
	s_barrier
	global_load_dwordx4 v[0:3], v[0:1], off
	s_nop 0
	global_load_dwordx4 v[4:7], v[4:5], off
	s_nop 0
	global_load_dwordx4 v[8:11], v[8:9], off
	s_nop 0
	global_load_dwordx4 v[12:15], v[12:13], off
	s_ashr_i32 s7, s6, 31
	v_mov_b32_e32 v88, 0
	s_lshl_b64 s[6:7], s[6:7], 16
	s_mov_b32 s1, -16
	v_mov_b32_e32 v69, v133
	v_mov_b32_e32 v89, v88
	v_mov_b32_e32 v90, v88
	v_mov_b32_e32 v91, v88
	v_mov_b32_e32 v94, v88
	v_mov_b32_e32 v95, v88
	v_mov_b32_e32 v98, v88
	v_mov_b32_e32 v99, v88
	v_mov_b32_e32 v104, v88
	v_mov_b32_e32 v105, v88
	v_mov_b32_e32 v102, v88
	v_mov_b32_e32 v103, v88
	v_mov_b32_e32 v92, v88
	v_mov_b32_e32 v93, v88
	v_mov_b32_e32 v96, v88
	v_mov_b32_e32 v97, v88
	v_mov_b32_e32 v32, v88
	v_mov_b32_e32 v33, v88
	v_mov_b32_e32 v36, v88
	v_mov_b32_e32 v37, v88
	v_mov_b32_e32 v40, v88
	v_mov_b32_e32 v41, v88
	v_mov_b32_e32 v86, v88
	v_mov_b32_e32 v87, v88
	v_mov_b32_e32 v106, v88
	v_mov_b32_e32 v107, v88
	v_mov_b32_e32 v34, v88
	v_mov_b32_e32 v35, v88
	v_mov_b32_e32 v38, v88
	v_mov_b32_e32 v39, v88
	v_mov_b32_e32 v42, v88
	v_lshl_add_u64 v[100:101], v[66:67], 0, s[6:7]
	v_mov_b32_e32 v43, v88
	v_readlane_b32 s70, v230, 2
	v_readlane_b32 s71, v230, 3
	v_readlane_b32 s72, v230, 4
	v_readlane_b32 s73, v230, 5
	v_readlane_b32 s74, v230, 6
	v_readlane_b32 s75, v230, 7
	v_readlane_b32 s76, v230, 8
	v_readlane_b32 s77, v230, 9
	v_readlane_b32 s78, v230, 10
	v_readlane_b32 s79, v230, 11
	v_readlane_b32 s80, v230, 12
	v_readlane_b32 s81, v230, 13
	v_readlane_b32 s82, v230, 14
	v_readlane_b32 s83, v230, 15
	s_waitcnt vmcnt(3)
	ds_write_b128 v119, v[0:3]
	s_waitcnt vmcnt(2)
	ds_write_b128 v123, v[4:7]
	s_waitcnt vmcnt(1)
	ds_write_b128 v127, v[8:11]
	s_waitcnt vmcnt(0)
	ds_write_b128 v131, v[12:15]
	s_mov_b32 s6, 0xfff7f000
	v_add_co_u32_e32 v0, vcc, s6, v100
	s_movk_i32 s6, 0xf000
	s_nop 0
	v_addc_co_u32_e32 v1, vcc, -1, v101, vcc
	global_load_dword v218, v[0:1], off offset:-3584
	v_add_co_u32_e32 v2, vcc, s6, v100
	s_mov_b32 s6, 0xfff80000
	s_nop 0
	v_addc_co_u32_e32 v3, vcc, -1, v101, vcc
	global_load_dword v219, v[2:3], off offset:-3584
	global_load_dword v220, v[0:1], off offset:-3072
	global_load_dword v221, v[2:3], off offset:-3072
	global_load_dword v222, v[0:1], off offset:-2560
	global_load_dword v223, v[2:3], off offset:-2560
	global_load_dword v224, v[0:1], off offset:-2048
	global_load_dword v225, v[2:3], off offset:-2048
	global_load_dword v226, v[0:1], off offset:-1536
	global_load_dword v227, v[2:3], off offset:-1536
	global_load_dword v228, v[0:1], off offset:-1024
	global_load_dword v229, v[2:3], off offset:-1024
	global_load_dword v232, v[0:1], off offset:-512
	global_load_dword v233, v[2:3], off offset:-512
	v_add_co_u32_e32 v0, vcc, s6, v100
	s_nop 0
	s_nop 0
	v_addc_co_u32_e32 v1, vcc, -1, v101, vcc
	global_load_dword v234, v[0:1], off offset:-4096
	global_load_dword v235, v[100:101], off offset:-4096
	global_load_dword v236, v[0:1], off offset:-3584
	global_load_dword v237, v[100:101], off offset:-3584
	global_load_dword v238, v[0:1], off offset:-3072
	global_load_dword v239, v[100:101], off offset:-3072
	global_load_dword v240, v[0:1], off offset:-2560
	global_load_dword v241, v[100:101], off offset:-2560
	global_load_dword v242, v[0:1], off offset:-2048
	global_load_dword v243, v[100:101], off offset:-2048
	global_load_dword v244, v[0:1], off offset:-1536
	global_load_dword v245, v[100:101], off offset:-1536
	global_load_dword v246, v[0:1], off offset:-1024
	global_load_dword v247, v[100:101], off offset:-1024
	global_load_dword v248, v[0:1], off offset:-512
	global_load_dword v249, v[100:101], off offset:-512
	global_load_dword v250, v[0:1], off
	global_load_dword v251, v[100:101], off
	s_mov_b64 s[6:7], 0x2000
	v_lshl_add_u64 v[100:101], v[100:101], 0, s[6:7]
	s_waitcnt lgkmcnt(0)
	s_barrier
; DEVI void compose_item(const P& p, int it, float* sm) {
;     ...
;     for (int d0 = 0; d0 < 128; d0 += 16) {
;         float cw[16], sw[16];
; #pragma unroll
;         for (int u = 0; u < 16; ++u) { cw[u] = wc[(d0 + u) * 128]; sw[u] = wsn[(d0 + u) * 128]; }
; #pragma unroll
;         for (int jj = 0; jj < 16; ++jj) {
; #pragma unroll
;             for (int u = 0; u < 16; u += 4) {
;                 const f32x4 v = *(const f32x4*)(sm + (half * 16 + jj) * 128 + d0 + u);
;                 ap[jj] += v[0] * cw[u] + v[1] * cw[u + 1] + v[2] * cw[u + 2] + v[3] * cw[u + 3];
;                 aq[jj] += v[0] * sw[u] + v[1] * sw[u + 1] + v[2] * sw[u + 2] + v[3] * sw[u + 3];
.LBB0_162:
	s_waitcnt vmcnt(0)
	v_mov_b32_e32 v164, v218
	v_mov_b32_e32 v122, v219
	v_mov_b32_e32 v168, v220
	v_mov_b32_e32 v124, v221
	v_mov_b32_e32 v166, v222
	v_mov_b32_e32 v126, v223
	v_mov_b32_e32 v162, v224
	v_mov_b32_e32 v130, v225
	v_mov_b32_e32 v158, v226
	v_mov_b32_e32 v128, v227
	v_mov_b32_e32 v160, v228
	v_mov_b32_e32 v132, v229
	v_mov_b32_e32 v154, v232
	v_mov_b32_e32 v134, v233
	v_mov_b32_e32 v156, v234
	v_mov_b32_e32 v136, v235
	v_mov_b32_e32 v150, v236
	v_mov_b32_e32 v114, v237
	v_mov_b32_e32 v152, v238
	v_mov_b32_e32 v120, v239
	v_mov_b32_e32 v148, v240
	v_mov_b32_e32 v116, v241
	v_mov_b32_e32 v146, v242
	v_mov_b32_e32 v118, v243
	v_mov_b32_e32 v142, v244
	v_mov_b32_e32 v110, v245
	v_mov_b32_e32 v144, v246
	v_mov_b32_e32 v112, v247
	v_mov_b32_e32 v140, v248
	v_mov_b32_e32 v108, v249
	v_mov_b32_e32 v138, v250
	v_mov_b32_e32 v44, v251
	s_add_i32 s1, s1, 16
	s_cmpk_lt_u32 s1, 0x70
	s_cbranch_scc0 .Lcmp_nopf
	s_mov_b32 s6, 0xfff7f000
	v_add_co_u32_e32 v0, vcc, s6, v100
	s_movk_i32 s6, 0xf000
	s_nop 0
	v_addc_co_u32_e32 v1, vcc, -1, v101, vcc
	global_load_dword v218, v[0:1], off offset:-3584
	v_add_co_u32_e32 v2, vcc, s6, v100
	s_mov_b32 s6, 0xfff80000
	s_nop 0
	v_addc_co_u32_e32 v3, vcc, -1, v101, vcc
	global_load_dword v219, v[2:3], off offset:-3584
	global_load_dword v220, v[0:1], off offset:-3072
	global_load_dword v221, v[2:3], off offset:-3072
	global_load_dword v222, v[0:1], off offset:-2560
	global_load_dword v223, v[2:3], off offset:-2560
	global_load_dword v224, v[0:1], off offset:-2048
	global_load_dword v225, v[2:3], off offset:-2048
	global_load_dword v226, v[0:1], off offset:-1536
	global_load_dword v227, v[2:3], off offset:-1536
	global_load_dword v228, v[0:1], off offset:-1024
	global_load_dword v229, v[2:3], off offset:-1024
	global_load_dword v232, v[0:1], off offset:-512
	global_load_dword v233, v[2:3], off offset:-512
	v_add_co_u32_e32 v0, vcc, s6, v100
	s_nop 0
	s_nop 0
	v_addc_co_u32_e32 v1, vcc, -1, v101, vcc
	global_load_dword v234, v[0:1], off offset:-4096
	global_load_dword v235, v[100:101], off offset:-4096
	global_load_dword v236, v[0:1], off offset:-3584
	global_load_dword v237, v[100:101], off offset:-3584
	global_load_dword v238, v[0:1], off offset:-3072
	global_load_dword v239, v[100:101], off offset:-3072
	global_load_dword v240, v[0:1], off offset:-2560
	global_load_dword v241, v[100:101], off offset:-2560
	global_load_dword v242, v[0:1], off offset:-2048
	global_load_dword v243, v[100:101], off offset:-2048
	global_load_dword v244, v[0:1], off offset:-1536
	global_load_dword v245, v[100:101], off offset:-1536
	global_load_dword v246, v[0:1], off offset:-1024
	global_load_dword v247, v[100:101], off offset:-1024
	global_load_dword v248, v[0:1], off offset:-512
	global_load_dword v249, v[100:101], off offset:-512
	global_load_dword v250, v[0:1], off
	global_load_dword v251, v[100:101], off
	s_mov_b64 s[6:7], 0x2000
	v_lshl_add_u64 v[100:101], v[100:101], 0, s[6:7]
.Lcmp_nopf:
	ds_read_b128 v[0:3], v69
	ds_read_b128 v[4:7], v69 offset:16
	ds_read_b128 v[8:11], v69 offset:32
	ds_read_b128 v[12:15], v69 offset:48
	ds_read_b128 v[16:19], v69 offset:512
	ds_read_b128 v[20:23], v69 offset:528
	ds_read_b128 v[24:27], v69 offset:544
	ds_read_b128 v[28:31], v69 offset:560
	s_waitcnt lgkmcnt(7)
	v_mov_b32_e32 v170, v0
	s_waitcnt lgkmcnt(3)
	v_mov_b32_e32 v171, v16
	v_mov_b32_e32 v16, v1
	v_mov_b32_e32 v185, v18
	v_mov_b32_e32 v18, v3
	s_waitcnt lgkmcnt(2)
	v_mov_b32_e32 v3, v20
	v_mov_b32_e32 v20, v5
	v_mov_b32_e32 v184, v2
	v_mov_b32_e32 v2, v4
	v_mov_b32_e32 v186, v6
	v_mov_b32_e32 v187, v22
	v_mov_b32_e32 v22, v7
	s_mov_b64 s[6:7], 0x2000
	s_cmpk_lt_u32 s1, 0x70
	v_pk_mul_f32 v[0:1], v[168:169], v[16:17] op_sel_hi:[0,1]
	v_pk_fma_f32 v[0:1], v[164:165], v[170:171], v[0:1] op_sel_hi:[0,1,1]
	v_pk_fma_f32 v[0:1], v[166:167], v[184:185], v[0:1] op_sel_hi:[0,1,1]
	v_pk_fma_f32 v[0:1], v[162:163], v[18:19], v[0:1] op_sel_hi:[0,1,1]
	v_pk_mul_f32 v[4:5], v[160:161], v[20:21] op_sel_hi:[0,1]
	v_pk_fma_f32 v[4:5], v[158:159], v[2:3], v[4:5] op_sel_hi:[0,1,1]
	v_pk_fma_f32 v[4:5], v[154:155], v[186:187], v[4:5] op_sel_hi:[0,1,1]
	v_pk_add_f32 v[0:1], v[98:99], v[0:1]
	v_pk_fma_f32 v[4:5], v[156:157], v[22:23], v[4:5] op_sel_hi:[0,1,1]
	v_pk_add_f32 v[0:1], v[0:1], v[4:5]
	s_waitcnt lgkmcnt(1)
	v_mov_b32_e32 v5, v24
	v_mov_b32_e32 v24, v9
	v_mov_b32_e32 v4, v8
	v_pk_mul_f32 v[6:7], v[152:153], v[24:25] op_sel_hi:[0,1]
	v_pk_fma_f32 v[6:7], v[150:151], v[4:5], v[6:7] op_sel_hi:[0,1,1]
	v_mov_b32_e32 v8, v10
	v_mov_b32_e32 v9, v26
	v_pk_fma_f32 v[6:7], v[148:149], v[8:9], v[6:7] op_sel_hi:[0,1,1]
	v_mov_b32_e32 v26, v11
	v_pk_fma_f32 v[6:7], v[146:147], v[26:27], v[6:7] op_sel_hi:[0,1,1]
	v_pk_add_f32 v[0:1], v[0:1], v[6:7]
	s_waitcnt lgkmcnt(0)
; DEVI void compose_item(const P& p, int it, float* sm) {
;     ...
; #pragma unroll
;         for (int jj = 0; jj < 16; ++jj) {
; #pragma unroll
;             for (int u = 0; u < 16; u += 4) {
;                 const f32x4 v = *(const f32x4*)(sm + (half * 16 + jj) * 128 + d0 + u);
;                 ap[jj] += v[0] * cw[u] + v[1] * cw[u + 1] + v[2] * cw[u + 2] + v[3] * cw[u + 3];
;                 aq[jj] += v[0] * sw[u] + v[1] * sw[u + 1] + v[2] * sw[u + 2] + v[3] * sw[u + 3];
;             }
;         }
	v_mov_b32_e32 v7, v28
	v_mov_b32_e32 v28, v13
	v_mov_b32_e32 v6, v12
	v_pk_mul_f32 v[10:11], v[144:145], v[28:29] op_sel_hi:[0,1]
	v_pk_fma_f32 v[10:11], v[142:143], v[6:7], v[10:11] op_sel_hi:[0,1,1]
	v_mov_b32_e32 v12, v14
	v_mov_b32_e32 v13, v30
	v_pk_fma_f32 v[10:11], v[140:141], v[12:13], v[10:11] op_sel_hi:[0,1,1]
	v_mov_b32_e32 v30, v15
	v_pk_fma_f32 v[10:11], v[138:139], v[30:31], v[10:11] op_sel_hi:[0,1,1]
	v_pk_add_f32 v[98:99], v[0:1], v[10:11]
	v_pk_mul_f32 v[0:1], v[124:125], v[16:17] op_sel_hi:[0,1]
	v_pk_fma_f32 v[0:1], v[122:123], v[170:171], v[0:1] op_sel_hi:[0,1,1]
	v_pk_mul_f32 v[10:11], v[132:133], v[20:21] op_sel_hi:[0,1]
	v_pk_fma_f32 v[0:1], v[126:127], v[184:185], v[0:1] op_sel_hi:[0,1,1]
	v_pk_fma_f32 v[2:3], v[128:129], v[2:3], v[10:11] op_sel_hi:[0,1,1]
	v_pk_fma_f32 v[0:1], v[130:131], v[18:19], v[0:1] op_sel_hi:[0,1,1]
	v_pk_fma_f32 v[2:3], v[134:135], v[186:187], v[2:3] op_sel_hi:[0,1,1]
	v_pk_add_f32 v[0:1], v[86:87], v[0:1]
	v_pk_fma_f32 v[2:3], v[136:137], v[22:23], v[2:3] op_sel_hi:[0,1,1]
	v_pk_add_f32 v[0:1], v[0:1], v[2:3]
	v_pk_mul_f32 v[2:3], v[120:121], v[24:25] op_sel_hi:[0,1]
	v_pk_fma_f32 v[2:3], v[114:115], v[4:5], v[2:3] op_sel_hi:[0,1,1]
	v_pk_fma_f32 v[2:3], v[116:117], v[8:9], v[2:3] op_sel_hi:[0,1,1]
	v_pk_fma_f32 v[2:3], v[118:119], v[26:27], v[2:3] op_sel_hi:[0,1,1]
	v_pk_add_f32 v[0:1], v[0:1], v[2:3]
	v_pk_mul_f32 v[2:3], v[112:113], v[28:29] op_sel_hi:[0,1]
	v_pk_fma_f32 v[2:3], v[110:111], v[6:7], v[2:3] op_sel_hi:[0,1,1]
	v_pk_fma_f32 v[2:3], v[108:109], v[12:13], v[2:3] op_sel_hi:[0,1,1]
	v_pk_fma_f32 v[2:3], v[44:45], v[30:31], v[2:3] op_sel_hi:[0,1,1]
	v_pk_add_f32 v[86:87], v[0:1], v[2:3]
	ds_read_b128 v[0:3], v69 offset:1024
	ds_read_b128 v[4:7], v69 offset:1040
	ds_read_b128 v[8:11], v69 offset:1056
	ds_read_b128 v[12:15], v69 offset:1072
	ds_read_b128 v[16:19], v69 offset:1536
	ds_read_b128 v[20:23], v69 offset:1552
	ds_read_b128 v[24:27], v69 offset:1568
	ds_read_b128 v[28:31], v69 offset:1584
	s_waitcnt lgkmcnt(7)
	v_mov_b32_e32 v170, v0
	s_waitcnt lgkmcnt(3)
	v_mov_b32_e32 v171, v16
	v_mov_b32_e32 v16, v1
	v_pk_mul_f32 v[0:1], v[168:169], v[16:17] op_sel_hi:[0,1]
	v_mov_b32_e32 v185, v18
	v_mov_b32_e32 v18, v3
	s_waitcnt lgkmcnt(2)
	v_mov_b32_e32 v3, v20
	v_mov_b32_e32 v20, v5
	v_pk_fma_f32 v[0:1], v[164:165], v[170:171], v[0:1] op_sel_hi:[0,1,1]
	v_mov_b32_e32 v184, v2
	v_mov_b32_e32 v2, v4
	v_pk_mul_f32 v[4:5], v[160:161], v[20:21] op_sel_hi:[0,1]
	v_pk_fma_f32 v[0:1], v[166:167], v[184:185], v[0:1] op_sel_hi:[0,1,1]
	v_pk_fma_f32 v[4:5], v[158:159], v[2:3], v[4:5] op_sel_hi:[0,1,1]
	v_mov_b32_e32 v186, v6
	v_mov_b32_e32 v187, v22
	v_pk_fma_f32 v[0:1], v[162:163], v[18:19], v[0:1] op_sel_hi:[0,1,1]
	v_pk_fma_f32 v[4:5], v[154:155], v[186:187], v[4:5] op_sel_hi:[0,1,1]
	v_mov_b32_e32 v22, v7
	v_pk_add_f32 v[0:1], v[94:95], v[0:1]
	v_pk_fma_f32 v[4:5], v[156:157], v[22:23], v[4:5] op_sel_hi:[0,1,1]
	v_pk_add_f32 v[0:1], v[0:1], v[4:5]
	s_waitcnt lgkmcnt(1)
	v_mov_b32_e32 v5, v24
	v_mov_b32_e32 v24, v9
	v_mov_b32_e32 v4, v8
	v_pk_mul_f32 v[6:7], v[152:153], v[24:25] op_sel_hi:[0,1]
	v_pk_fma_f32 v[6:7], v[150:151], v[4:5], v[6:7] op_sel_hi:[0,1,1]
	v_mov_b32_e32 v8, v10
	v_mov_b32_e32 v9, v26
	v_pk_fma_f32 v[6:7], v[148:149], v[8:9], v[6:7] op_sel_hi:[0,1,1]
	v_mov_b32_e32 v26, v11
	v_pk_fma_f32 v[6:7], v[146:147], v[26:27], v[6:7] op_sel_hi:[0,1,1]
	v_pk_add_f32 v[0:1], v[0:1], v[6:7]
	s_waitcnt lgkmcnt(0)
	v_mov_b32_e32 v7, v28
	v_mov_b32_e32 v28, v13
	v_mov_b32_e32 v6, v12
	v_pk_mul_f32 v[10:11], v[144:145], v[28:29] op_sel_hi:[0,1]
	v_pk_fma_f32 v[10:11], v[142:143], v[6:7], v[10:11] op_sel_hi:[0,1,1]
	v_mov_b32_e32 v12, v14
	v_mov_b32_e32 v13, v30
	v_pk_fma_f32 v[10:11], v[140:141], v[12:13], v[10:11] op_sel_hi:[0,1,1]
	v_mov_b32_e32 v30, v15
	v_pk_fma_f32 v[10:11], v[138:139], v[30:31], v[10:11] op_sel_hi:[0,1,1]
	v_pk_add_f32 v[94:95], v[0:1], v[10:11]
	v_pk_mul_f32 v[0:1], v[124:125], v[16:17] op_sel_hi:[0,1]
	v_pk_fma_f32 v[0:1], v[122:123], v[170:171], v[0:1] op_sel_hi:[0,1,1]
	v_pk_mul_f32 v[10:11], v[132:133], v[20:21] op_sel_hi:[0,1]
	v_pk_fma_f32 v[0:1], v[126:127], v[184:185], v[0:1] op_sel_hi:[0,1,1]
	v_pk_fma_f32 v[2:3], v[128:129], v[2:3], v[10:11] op_sel_hi:[0,1,1]
	v_pk_fma_f32 v[0:1], v[130:131], v[18:19], v[0:1] op_sel_hi:[0,1,1]
	v_pk_fma_f32 v[2:3], v[134:135], v[186:187], v[2:3] op_sel_hi:[0,1,1]
	v_pk_add_f32 v[0:1], v[40:41], v[0:1]
	v_pk_fma_f32 v[2:3], v[136:137], v[22:23], v[2:3] op_sel_hi:[0,1,1]
	v_pk_add_f32 v[0:1], v[0:1], v[2:3]
	v_pk_mul_f32 v[2:3], v[120:121], v[24:25] op_sel_hi:[0,1]
	v_pk_fma_f32 v[2:3], v[114:115], v[4:5], v[2:3] op_sel_hi:[0,1,1]
	v_pk_fma_f32 v[2:3], v[116:117], v[8:9], v[2:3] op_sel_hi:[0,1,1]
	v_pk_fma_f32 v[2:3], v[118:119], v[26:27], v[2:3] op_sel_hi:[0,1,1]
	v_pk_add_f32 v[0:1], v[0:1], v[2:3]
	v_pk_mul_f32 v[2:3], v[112:113], v[28:29] op_sel_hi:[0,1]
	v_pk_fma_f32 v[2:3], v[110:111], v[6:7], v[2:3] op_sel_hi:[0,1,1]
	v_pk_fma_f32 v[2:3], v[108:109], v[12:13], v[2:3] op_sel_hi:[0,1,1]
	v_pk_fma_f32 v[2:3], v[44:45], v[30:31], v[2:3] op_sel_hi:[0,1,1]
	v_pk_add_f32 v[40:41], v[0:1], v[2:3]
	ds_read_b128 v[0:3], v69 offset:2048
	ds_read_b128 v[4:7], v69 offset:2064
	ds_read_b128 v[8:11], v69 offset:2080
	ds_read_b128 v[12:15], v69 offset:2096
	ds_read_b128 v[16:19], v69 offset:2560
	ds_read_b128 v[20:23], v69 offset:2576
	ds_read_b128 v[24:27], v69 offset:2592
	ds_read_b128 v[28:31], v69 offset:2608
	s_waitcnt lgkmcnt(7)
	v_mov_b32_e32 v170, v0
	s_waitcnt lgkmcnt(3)
	v_mov_b32_e32 v171, v16
	v_mov_b32_e32 v16, v1
	v_pk_mul_f32 v[0:1], v[168:169], v[16:17] op_sel_hi:[0,1]
	v_mov_b32_e32 v185, v18
	v_mov_b32_e32 v18, v3
	s_waitcnt lgkmcnt(2)
; DEVI void compose_item(const P& p, int it, float* sm) {
;     ...
; #pragma unroll
;         for (int jj = 0; jj < 16; ++jj) {
; #pragma unroll
;             for (int u = 0; u < 16; u += 4) {
;                 const f32x4 v = *(const f32x4*)(sm + (half * 16 + jj) * 128 + d0 + u);
;                 ap[jj] += v[0] * cw[u] + v[1] * cw[u + 1] + v[2] * cw[u + 2] + v[3] * cw[u + 3];
;                 aq[jj] += v[0] * sw[u] + v[1] * sw[u + 1] + v[2] * sw[u + 2] + v[3] * sw[u + 3];
;             }
;         }
	v_mov_b32_e32 v3, v20
	v_mov_b32_e32 v20, v5
	v_pk_fma_f32 v[0:1], v[164:165], v[170:171], v[0:1] op_sel_hi:[0,1,1]
	v_mov_b32_e32 v184, v2
	v_mov_b32_e32 v2, v4
	v_pk_mul_f32 v[4:5], v[160:161], v[20:21] op_sel_hi:[0,1]
	v_pk_fma_f32 v[0:1], v[166:167], v[184:185], v[0:1] op_sel_hi:[0,1,1]
	v_pk_fma_f32 v[4:5], v[158:159], v[2:3], v[4:5] op_sel_hi:[0,1,1]
	v_mov_b32_e32 v186, v6
	v_mov_b32_e32 v187, v22
	v_pk_fma_f32 v[0:1], v[162:163], v[18:19], v[0:1] op_sel_hi:[0,1,1]
	v_pk_fma_f32 v[4:5], v[154:155], v[186:187], v[4:5] op_sel_hi:[0,1,1]
	v_mov_b32_e32 v22, v7
	v_pk_add_f32 v[0:1], v[90:91], v[0:1]
	v_pk_fma_f32 v[4:5], v[156:157], v[22:23], v[4:5] op_sel_hi:[0,1,1]
	v_pk_add_f32 v[0:1], v[0:1], v[4:5]
	s_waitcnt lgkmcnt(1)
	v_mov_b32_e32 v5, v24
	v_mov_b32_e32 v24, v9
	v_mov_b32_e32 v4, v8
	v_pk_mul_f32 v[6:7], v[152:153], v[24:25] op_sel_hi:[0,1]
	v_pk_fma_f32 v[6:7], v[150:151], v[4:5], v[6:7] op_sel_hi:[0,1,1]
	v_mov_b32_e32 v8, v10
	v_mov_b32_e32 v9, v26
	v_pk_fma_f32 v[6:7], v[148:149], v[8:9], v[6:7] op_sel_hi:[0,1,1]
	v_mov_b32_e32 v26, v11
	v_pk_fma_f32 v[6:7], v[146:147], v[26:27], v[6:7] op_sel_hi:[0,1,1]
	v_pk_add_f32 v[0:1], v[0:1], v[6:7]
	s_waitcnt lgkmcnt(0)
	v_mov_b32_e32 v7, v28
	v_mov_b32_e32 v28, v13
	v_mov_b32_e32 v6, v12
	v_pk_mul_f32 v[10:11], v[144:145], v[28:29] op_sel_hi:[0,1]
	v_pk_fma_f32 v[10:11], v[142:143], v[6:7], v[10:11] op_sel_hi:[0,1,1]
	v_mov_b32_e32 v12, v14
	v_mov_b32_e32 v13, v30
	v_pk_fma_f32 v[10:11], v[140:141], v[12:13], v[10:11] op_sel_hi:[0,1,1]
	v_mov_b32_e32 v30, v15
	v_pk_fma_f32 v[10:11], v[138:139], v[30:31], v[10:11] op_sel_hi:[0,1,1]
	v_pk_add_f32 v[90:91], v[0:1], v[10:11]
	v_pk_mul_f32 v[0:1], v[124:125], v[16:17] op_sel_hi:[0,1]
	v_pk_fma_f32 v[0:1], v[122:123], v[170:171], v[0:1] op_sel_hi:[0,1,1]
	v_pk_mul_f32 v[10:11], v[132:133], v[20:21] op_sel_hi:[0,1]
	v_pk_fma_f32 v[0:1], v[126:127], v[184:185], v[0:1] op_sel_hi:[0,1,1]
	v_pk_fma_f32 v[2:3], v[128:129], v[2:3], v[10:11] op_sel_hi:[0,1,1]
	v_pk_fma_f32 v[0:1], v[130:131], v[18:19], v[0:1] op_sel_hi:[0,1,1]
	v_pk_fma_f32 v[2:3], v[134:135], v[186:187], v[2:3] op_sel_hi:[0,1,1]
	v_pk_add_f32 v[0:1], v[36:37], v[0:1]
	v_pk_fma_f32 v[2:3], v[136:137], v[22:23], v[2:3] op_sel_hi:[0,1,1]
	v_pk_add_f32 v[0:1], v[0:1], v[2:3]
	v_pk_mul_f32 v[2:3], v[120:121], v[24:25] op_sel_hi:[0,1]
	v_pk_fma_f32 v[2:3], v[114:115], v[4:5], v[2:3] op_sel_hi:[0,1,1]
	v_pk_fma_f32 v[2:3], v[116:117], v[8:9], v[2:3] op_sel_hi:[0,1,1]
	v_pk_fma_f32 v[2:3], v[118:119], v[26:27], v[2:3] op_sel_hi:[0,1,1]
	v_pk_add_f32 v[0:1], v[0:1], v[2:3]
	v_pk_mul_f32 v[2:3], v[112:113], v[28:29] op_sel_hi:[0,1]
	v_pk_fma_f32 v[2:3], v[110:111], v[6:7], v[2:3] op_sel_hi:[0,1,1]
	v_pk_fma_f32 v[2:3], v[108:109], v[12:13], v[2:3] op_sel_hi:[0,1,1]
	v_pk_fma_f32 v[2:3], v[44:45], v[30:31], v[2:3] op_sel_hi:[0,1,1]
	v_pk_add_f32 v[36:37], v[0:1], v[2:3]
	ds_read_b128 v[0:3], v69 offset:3072
	ds_read_b128 v[4:7], v69 offset:3088
	ds_read_b128 v[8:11], v69 offset:3104
	ds_read_b128 v[12:15], v69 offset:3120
	ds_read_b128 v[16:19], v69 offset:3584
	ds_read_b128 v[20:23], v69 offset:3600
	ds_read_b128 v[24:27], v69 offset:3616
	ds_read_b128 v[28:31], v69 offset:3632
	s_waitcnt lgkmcnt(7)
	v_mov_b32_e32 v170, v0
	s_waitcnt lgkmcnt(3)
	v_mov_b32_e32 v171, v16
	v_mov_b32_e32 v16, v1
	v_pk_mul_f32 v[0:1], v[168:169], v[16:17] op_sel_hi:[0,1]
	v_mov_b32_e32 v185, v18
	v_mov_b32_e32 v18, v3
	s_waitcnt lgkmcnt(2)
	v_mov_b32_e32 v3, v20
	v_mov_b32_e32 v20, v5
	v_pk_fma_f32 v[0:1], v[164:165], v[170:171], v[0:1] op_sel_hi:[0,1,1]
	v_mov_b32_e32 v184, v2
	v_mov_b32_e32 v2, v4
	v_pk_mul_f32 v[4:5], v[160:161], v[20:21] op_sel_hi:[0,1]
	v_pk_fma_f32 v[0:1], v[166:167], v[184:185], v[0:1] op_sel_hi:[0,1,1]
	v_pk_fma_f32 v[4:5], v[158:159], v[2:3], v[4:5] op_sel_hi:[0,1,1]
	v_mov_b32_e32 v186, v6
	v_mov_b32_e32 v187, v22
	v_pk_fma_f32 v[0:1], v[162:163], v[18:19], v[0:1] op_sel_hi:[0,1,1]
	v_pk_fma_f32 v[4:5], v[154:155], v[186:187], v[4:5] op_sel_hi:[0,1,1]
	v_mov_b32_e32 v22, v7
	v_pk_add_f32 v[0:1], v[88:89], v[0:1]
	v_pk_fma_f32 v[4:5], v[156:157], v[22:23], v[4:5] op_sel_hi:[0,1,1]
	v_pk_add_f32 v[0:1], v[0:1], v[4:5]
	s_waitcnt lgkmcnt(1)
	v_mov_b32_e32 v5, v24
	v_mov_b32_e32 v24, v9
	v_mov_b32_e32 v4, v8
	v_pk_mul_f32 v[6:7], v[152:153], v[24:25] op_sel_hi:[0,1]
	v_pk_fma_f32 v[6:7], v[150:151], v[4:5], v[6:7] op_sel_hi:[0,1,1]
	v_mov_b32_e32 v8, v10
	v_mov_b32_e32 v9, v26
	v_pk_fma_f32 v[6:7], v[148:149], v[8:9], v[6:7] op_sel_hi:[0,1,1]
	v_mov_b32_e32 v26, v11
	v_pk_fma_f32 v[6:7], v[146:147], v[26:27], v[6:7] op_sel_hi:[0,1,1]
	v_pk_add_f32 v[0:1], v[0:1], v[6:7]
	s_waitcnt lgkmcnt(0)
; DEVI void compose_item(const P& p, int it, float* sm) {
;     ...
; #pragma unroll
;         for (int jj = 0; jj < 16; ++jj) {
; #pragma unroll
;             for (int u = 0; u < 16; u += 4) {
;                 const f32x4 v = *(const f32x4*)(sm + (half * 16 + jj) * 128 + d0 + u);
;                 ap[jj] += v[0] * cw[u] + v[1] * cw[u + 1] + v[2] * cw[u + 2] + v[3] * cw[u + 3];
;                 aq[jj] += v[0] * sw[u] + v[1] * sw[u + 1] + v[2] * sw[u + 2] + v[3] * sw[u + 3];
;             }
;         }
	v_mov_b32_e32 v7, v28
	v_mov_b32_e32 v28, v13
	v_mov_b32_e32 v6, v12
	v_pk_mul_f32 v[10:11], v[144:145], v[28:29] op_sel_hi:[0,1]
	v_pk_fma_f32 v[10:11], v[142:143], v[6:7], v[10:11] op_sel_hi:[0,1,1]
	v_mov_b32_e32 v12, v14
	v_mov_b32_e32 v13, v30
	v_pk_fma_f32 v[10:11], v[140:141], v[12:13], v[10:11] op_sel_hi:[0,1,1]
	v_mov_b32_e32 v30, v15
	v_pk_fma_f32 v[10:11], v[138:139], v[30:31], v[10:11] op_sel_hi:[0,1,1]
	v_pk_add_f32 v[88:89], v[0:1], v[10:11]
	v_pk_mul_f32 v[0:1], v[124:125], v[16:17] op_sel_hi:[0,1]
	v_pk_fma_f32 v[0:1], v[122:123], v[170:171], v[0:1] op_sel_hi:[0,1,1]
	v_pk_mul_f32 v[10:11], v[132:133], v[20:21] op_sel_hi:[0,1]
	v_pk_fma_f32 v[0:1], v[126:127], v[184:185], v[0:1] op_sel_hi:[0,1,1]
	v_pk_fma_f32 v[2:3], v[128:129], v[2:3], v[10:11] op_sel_hi:[0,1,1]
	v_pk_fma_f32 v[0:1], v[130:131], v[18:19], v[0:1] op_sel_hi:[0,1,1]
	v_pk_fma_f32 v[2:3], v[134:135], v[186:187], v[2:3] op_sel_hi:[0,1,1]
	v_pk_add_f32 v[0:1], v[32:33], v[0:1]
	v_pk_fma_f32 v[2:3], v[136:137], v[22:23], v[2:3] op_sel_hi:[0,1,1]
	v_pk_add_f32 v[0:1], v[0:1], v[2:3]
	v_pk_mul_f32 v[2:3], v[120:121], v[24:25] op_sel_hi:[0,1]
	v_pk_fma_f32 v[2:3], v[114:115], v[4:5], v[2:3] op_sel_hi:[0,1,1]
	v_pk_fma_f32 v[2:3], v[116:117], v[8:9], v[2:3] op_sel_hi:[0,1,1]
	v_pk_fma_f32 v[2:3], v[118:119], v[26:27], v[2:3] op_sel_hi:[0,1,1]
	v_pk_add_f32 v[0:1], v[0:1], v[2:3]
	v_pk_mul_f32 v[2:3], v[112:113], v[28:29] op_sel_hi:[0,1]
	v_pk_fma_f32 v[2:3], v[110:111], v[6:7], v[2:3] op_sel_hi:[0,1,1]
	v_pk_fma_f32 v[2:3], v[108:109], v[12:13], v[2:3] op_sel_hi:[0,1,1]
	v_pk_fma_f32 v[2:3], v[44:45], v[30:31], v[2:3] op_sel_hi:[0,1,1]
	v_pk_add_f32 v[32:33], v[0:1], v[2:3]
	ds_read_b128 v[0:3], v69 offset:4096
	ds_read_b128 v[4:7], v69 offset:4112
	ds_read_b128 v[8:11], v69 offset:4128
	ds_read_b128 v[12:15], v69 offset:4144
	ds_read_b128 v[16:19], v69 offset:4608
	ds_read_b128 v[20:23], v69 offset:4624
	ds_read_b128 v[24:27], v69 offset:4640
	ds_read_b128 v[28:31], v69 offset:4656
	s_waitcnt lgkmcnt(7)
	v_mov_b32_e32 v170, v0
	s_waitcnt lgkmcnt(3)
	v_mov_b32_e32 v171, v16
	v_mov_b32_e32 v16, v1
	v_pk_mul_f32 v[0:1], v[168:169], v[16:17] op_sel_hi:[0,1]
	v_mov_b32_e32 v185, v18
	v_mov_b32_e32 v18, v3
	s_waitcnt lgkmcnt(2)
	v_mov_b32_e32 v3, v20
	v_mov_b32_e32 v20, v5
	v_pk_fma_f32 v[0:1], v[164:165], v[170:171], v[0:1] op_sel_hi:[0,1,1]
	v_mov_b32_e32 v184, v2
	v_mov_b32_e32 v2, v4
	v_pk_mul_f32 v[4:5], v[160:161], v[20:21] op_sel_hi:[0,1]
	v_pk_fma_f32 v[0:1], v[166:167], v[184:185], v[0:1] op_sel_hi:[0,1,1]
	v_pk_fma_f32 v[4:5], v[158:159], v[2:3], v[4:5] op_sel_hi:[0,1,1]
	v_mov_b32_e32 v186, v6
	v_mov_b32_e32 v187, v22
	v_pk_fma_f32 v[0:1], v[162:163], v[18:19], v[0:1] op_sel_hi:[0,1,1]
	v_pk_fma_f32 v[4:5], v[154:155], v[186:187], v[4:5] op_sel_hi:[0,1,1]
	v_mov_b32_e32 v22, v7
	v_pk_add_f32 v[0:1], v[96:97], v[0:1]
	v_pk_fma_f32 v[4:5], v[156:157], v[22:23], v[4:5] op_sel_hi:[0,1,1]
	v_pk_add_f32 v[0:1], v[0:1], v[4:5]
	s_waitcnt lgkmcnt(1)
	v_mov_b32_e32 v5, v24
	v_mov_b32_e32 v24, v9
	v_mov_b32_e32 v4, v8
	v_pk_mul_f32 v[6:7], v[152:153], v[24:25] op_sel_hi:[0,1]
	v_pk_fma_f32 v[6:7], v[150:151], v[4:5], v[6:7] op_sel_hi:[0,1,1]
	v_mov_b32_e32 v8, v10
	v_mov_b32_e32 v9, v26
	v_pk_fma_f32 v[6:7], v[148:149], v[8:9], v[6:7] op_sel_hi:[0,1,1]
	v_mov_b32_e32 v26, v11
	v_pk_fma_f32 v[6:7], v[146:147], v[26:27], v[6:7] op_sel_hi:[0,1,1]
	v_pk_add_f32 v[0:1], v[0:1], v[6:7]
	s_waitcnt lgkmcnt(0)
	v_mov_b32_e32 v7, v28
	v_mov_b32_e32 v28, v13
	v_mov_b32_e32 v6, v12
	v_pk_mul_f32 v[10:11], v[144:145], v[28:29] op_sel_hi:[0,1]
	v_pk_fma_f32 v[10:11], v[142:143], v[6:7], v[10:11] op_sel_hi:[0,1,1]
	v_mov_b32_e32 v12, v14
	v_mov_b32_e32 v13, v30
	v_pk_fma_f32 v[10:11], v[140:141], v[12:13], v[10:11] op_sel_hi:[0,1,1]
	v_mov_b32_e32 v30, v15
	v_pk_fma_f32 v[10:11], v[138:139], v[30:31], v[10:11] op_sel_hi:[0,1,1]
	v_pk_add_f32 v[96:97], v[0:1], v[10:11]
	v_pk_mul_f32 v[0:1], v[124:125], v[16:17] op_sel_hi:[0,1]
	v_pk_fma_f32 v[0:1], v[122:123], v[170:171], v[0:1] op_sel_hi:[0,1,1]
	v_pk_mul_f32 v[10:11], v[132:133], v[20:21] op_sel_hi:[0,1]
	v_pk_fma_f32 v[0:1], v[126:127], v[184:185], v[0:1] op_sel_hi:[0,1,1]
	v_pk_fma_f32 v[2:3], v[128:129], v[2:3], v[10:11] op_sel_hi:[0,1,1]
	v_pk_fma_f32 v[0:1], v[130:131], v[18:19], v[0:1] op_sel_hi:[0,1,1]
	v_pk_fma_f32 v[2:3], v[134:135], v[186:187], v[2:3] op_sel_hi:[0,1,1]
	v_pk_add_f32 v[0:1], v[42:43], v[0:1]
	v_pk_fma_f32 v[2:3], v[136:137], v[22:23], v[2:3] op_sel_hi:[0,1,1]
	v_pk_add_f32 v[0:1], v[0:1], v[2:3]
	v_pk_mul_f32 v[2:3], v[120:121], v[24:25] op_sel_hi:[0,1]
	v_pk_fma_f32 v[2:3], v[114:115], v[4:5], v[2:3] op_sel_hi:[0,1,1]
	v_pk_fma_f32 v[2:3], v[116:117], v[8:9], v[2:3] op_sel_hi:[0,1,1]
	v_pk_fma_f32 v[2:3], v[118:119], v[26:27], v[2:3] op_sel_hi:[0,1,1]
	v_pk_add_f32 v[0:1], v[0:1], v[2:3]
	v_pk_mul_f32 v[2:3], v[112:113], v[28:29] op_sel_hi:[0,1]
	v_pk_fma_f32 v[2:3], v[110:111], v[6:7], v[2:3] op_sel_hi:[0,1,1]
	v_pk_fma_f32 v[2:3], v[108:109], v[12:13], v[2:3] op_sel_hi:[0,1,1]
	v_pk_fma_f32 v[2:3], v[44:45], v[30:31], v[2:3] op_sel_hi:[0,1,1]
	v_pk_add_f32 v[42:43], v[0:1], v[2:3]
	ds_read_b128 v[0:3], v69 offset:5120
	ds_read_b128 v[4:7], v69 offset:5136
	ds_read_b128 v[8:11], v69 offset:5152
	ds_read_b128 v[12:15], v69 offset:5168
	ds_read_b128 v[16:19], v69 offset:5632
	ds_read_b128 v[20:23], v69 offset:5648
	ds_read_b128 v[24:27], v69 offset:5664
	ds_read_b128 v[28:31], v69 offset:5680
	s_waitcnt lgkmcnt(7)
	v_mov_b32_e32 v170, v0
	s_waitcnt lgkmcnt(3)
	v_mov_b32_e32 v171, v16
	v_mov_b32_e32 v16, v1
	v_pk_mul_f32 v[0:1], v[168:169], v[16:17] op_sel_hi:[0,1]
	v_mov_b32_e32 v185, v18
	v_mov_b32_e32 v18, v3
	s_waitcnt lgkmcnt(2)
; DEVI void compose_item(const P& p, int it, float* sm) {
;     ...
; #pragma unroll
;         for (int jj = 0; jj < 16; ++jj) {
; #pragma unroll
;             for (int u = 0; u < 16; u += 4) {
;                 const f32x4 v = *(const f32x4*)(sm + (half * 16 + jj) * 128 + d0 + u);
;                 ap[jj] += v[0] * cw[u] + v[1] * cw[u + 1] + v[2] * cw[u + 2] + v[3] * cw[u + 3];
;                 aq[jj] += v[0] * sw[u] + v[1] * sw[u + 1] + v[2] * sw[u + 2] + v[3] * sw[u + 3];
;             }
;         }
	v_mov_b32_e32 v3, v20
	v_mov_b32_e32 v20, v5
	v_pk_fma_f32 v[0:1], v[164:165], v[170:171], v[0:1] op_sel_hi:[0,1,1]
	v_mov_b32_e32 v184, v2
	v_mov_b32_e32 v2, v4
	v_pk_mul_f32 v[4:5], v[160:161], v[20:21] op_sel_hi:[0,1]
	v_pk_fma_f32 v[0:1], v[166:167], v[184:185], v[0:1] op_sel_hi:[0,1,1]
	v_pk_fma_f32 v[4:5], v[158:159], v[2:3], v[4:5] op_sel_hi:[0,1,1]
	v_mov_b32_e32 v186, v6
	v_mov_b32_e32 v187, v22
	v_pk_fma_f32 v[0:1], v[162:163], v[18:19], v[0:1] op_sel_hi:[0,1,1]
	v_pk_fma_f32 v[4:5], v[154:155], v[186:187], v[4:5] op_sel_hi:[0,1,1]
	v_mov_b32_e32 v22, v7
	v_pk_add_f32 v[0:1], v[92:93], v[0:1]
	v_pk_fma_f32 v[4:5], v[156:157], v[22:23], v[4:5] op_sel_hi:[0,1,1]
	v_pk_add_f32 v[0:1], v[0:1], v[4:5]
	s_waitcnt lgkmcnt(1)
	v_mov_b32_e32 v5, v24
	v_mov_b32_e32 v24, v9
	v_mov_b32_e32 v4, v8
	v_pk_mul_f32 v[6:7], v[152:153], v[24:25] op_sel_hi:[0,1]
	v_pk_fma_f32 v[6:7], v[150:151], v[4:5], v[6:7] op_sel_hi:[0,1,1]
	v_mov_b32_e32 v8, v10
	v_mov_b32_e32 v9, v26
	v_pk_fma_f32 v[6:7], v[148:149], v[8:9], v[6:7] op_sel_hi:[0,1,1]
	v_mov_b32_e32 v26, v11
	v_pk_fma_f32 v[6:7], v[146:147], v[26:27], v[6:7] op_sel_hi:[0,1,1]
	v_pk_add_f32 v[0:1], v[0:1], v[6:7]
	s_waitcnt lgkmcnt(0)
	v_mov_b32_e32 v7, v28
	v_mov_b32_e32 v28, v13
	v_mov_b32_e32 v6, v12
	v_pk_mul_f32 v[10:11], v[144:145], v[28:29] op_sel_hi:[0,1]
	v_pk_fma_f32 v[10:11], v[142:143], v[6:7], v[10:11] op_sel_hi:[0,1,1]
	v_mov_b32_e32 v12, v14
	v_mov_b32_e32 v13, v30
	v_pk_fma_f32 v[10:11], v[140:141], v[12:13], v[10:11] op_sel_hi:[0,1,1]
	v_mov_b32_e32 v30, v15
	v_pk_fma_f32 v[10:11], v[138:139], v[30:31], v[10:11] op_sel_hi:[0,1,1]
	v_pk_add_f32 v[92:93], v[0:1], v[10:11]
	v_pk_mul_f32 v[0:1], v[124:125], v[16:17] op_sel_hi:[0,1]
	v_pk_fma_f32 v[0:1], v[122:123], v[170:171], v[0:1] op_sel_hi:[0,1,1]
	v_pk_mul_f32 v[10:11], v[132:133], v[20:21] op_sel_hi:[0,1]
	v_pk_fma_f32 v[0:1], v[126:127], v[184:185], v[0:1] op_sel_hi:[0,1,1]
	v_pk_fma_f32 v[2:3], v[128:129], v[2:3], v[10:11] op_sel_hi:[0,1,1]
	v_pk_fma_f32 v[0:1], v[130:131], v[18:19], v[0:1] op_sel_hi:[0,1,1]
	v_pk_fma_f32 v[2:3], v[134:135], v[186:187], v[2:3] op_sel_hi:[0,1,1]
	v_pk_add_f32 v[0:1], v[38:39], v[0:1]
	v_pk_fma_f32 v[2:3], v[136:137], v[22:23], v[2:3] op_sel_hi:[0,1,1]
	v_pk_add_f32 v[0:1], v[0:1], v[2:3]
	v_pk_mul_f32 v[2:3], v[120:121], v[24:25] op_sel_hi:[0,1]
	v_pk_fma_f32 v[2:3], v[114:115], v[4:5], v[2:3] op_sel_hi:[0,1,1]
	v_pk_fma_f32 v[2:3], v[116:117], v[8:9], v[2:3] op_sel_hi:[0,1,1]
	v_pk_fma_f32 v[2:3], v[118:119], v[26:27], v[2:3] op_sel_hi:[0,1,1]
	v_pk_add_f32 v[0:1], v[0:1], v[2:3]
	v_pk_mul_f32 v[2:3], v[112:113], v[28:29] op_sel_hi:[0,1]
	v_pk_fma_f32 v[2:3], v[110:111], v[6:7], v[2:3] op_sel_hi:[0,1,1]
	v_pk_fma_f32 v[2:3], v[108:109], v[12:13], v[2:3] op_sel_hi:[0,1,1]
	v_pk_fma_f32 v[2:3], v[44:45], v[30:31], v[2:3] op_sel_hi:[0,1,1]
	v_pk_add_f32 v[38:39], v[0:1], v[2:3]
	ds_read_b128 v[4:7], v69 offset:6144
	ds_read_b128 v[0:3], v69 offset:6160
	ds_read_b128 v[28:31], v69 offset:6176
	ds_read_b128 v[24:27], v69 offset:6192
	ds_read_b128 v[20:23], v69 offset:6656
	ds_read_b128 v[16:19], v69 offset:6672
	ds_read_b128 v[12:15], v69 offset:6688
	ds_read_b128 v[8:11], v69 offset:6704
	s_waitcnt lgkmcnt(7)
	v_mov_b32_e32 v170, v4
	s_waitcnt lgkmcnt(3)
	v_mov_b32_e32 v171, v20
	v_mov_b32_e32 v20, v5
	v_pk_mul_f32 v[4:5], v[168:169], v[20:21] op_sel_hi:[0,1]
	v_mov_b32_e32 v185, v22
	v_mov_b32_e32 v22, v7
	s_waitcnt lgkmcnt(2)
	v_mov_b32_e32 v7, v16
	v_mov_b32_e32 v16, v1
	v_pk_fma_f32 v[4:5], v[164:165], v[170:171], v[4:5] op_sel_hi:[0,1,1]
	v_mov_b32_e32 v184, v6
	v_mov_b32_e32 v6, v0
	v_pk_mul_f32 v[0:1], v[160:161], v[16:17] op_sel_hi:[0,1]
	v_pk_fma_f32 v[4:5], v[166:167], v[184:185], v[4:5] op_sel_hi:[0,1,1]
	v_pk_fma_f32 v[0:1], v[158:159], v[6:7], v[0:1] op_sel_hi:[0,1,1]
	v_mov_b32_e32 v186, v2
	v_mov_b32_e32 v187, v18
	v_pk_fma_f32 v[4:5], v[162:163], v[22:23], v[4:5] op_sel_hi:[0,1,1]
	v_pk_fma_f32 v[0:1], v[154:155], v[186:187], v[0:1] op_sel_hi:[0,1,1]
	v_mov_b32_e32 v18, v3
	v_pk_add_f32 v[4:5], v[102:103], v[4:5]
	v_pk_fma_f32 v[0:1], v[156:157], v[18:19], v[0:1] op_sel_hi:[0,1,1]
	s_waitcnt lgkmcnt(1)
	v_mov_b32_e32 v3, v12
	v_mov_b32_e32 v12, v29
	v_pk_add_f32 v[0:1], v[4:5], v[0:1]
	v_mov_b32_e32 v2, v28
	v_pk_mul_f32 v[4:5], v[152:153], v[12:13] op_sel_hi:[0,1]
	v_pk_fma_f32 v[4:5], v[150:151], v[2:3], v[4:5] op_sel_hi:[0,1,1]
	v_mov_b32_e32 v28, v30
	v_mov_b32_e32 v29, v14
	v_pk_fma_f32 v[4:5], v[148:149], v[28:29], v[4:5] op_sel_hi:[0,1,1]
	v_mov_b32_e32 v14, v31
	v_pk_fma_f32 v[4:5], v[146:147], v[14:15], v[4:5] op_sel_hi:[0,1,1]
	v_pk_add_f32 v[0:1], v[0:1], v[4:5]
	s_waitcnt lgkmcnt(0)
; DEVI unsigned pk2(float lo, float hi) { f32x2 v = {lo, hi}; bf16x2_t b = __builtin_convertvector(v, bf16x2_t); return __builtin_bit_cast(unsigned, b); }
; DEVI void compose_item(const P& p, int it, float* sm) {
;     ...
; #pragma unroll
;         for (int jj = 0; jj < 16; ++jj) {
; #pragma unroll
;             for (int u = 0; u < 16; u += 4) {
;                 const f32x4 v = *(const f32x4*)(sm + (half * 16 + jj) * 128 + d0 + u);
;                 ap[jj] += v[0] * cw[u] + v[1] * cw[u + 1] + v[2] * cw[u + 2] + v[3] * cw[u + 3];
;                 aq[jj] += v[0] * sw[u] + v[1] * sw[u + 1] + v[2] * sw[u + 2] + v[3] * sw[u + 3];
;             }
;         }
;     }
;     bf16_t* W0T = (bf16_t*)(p.ws + OFF_W0T);
;     bf16_t* dp = W0T + (size_t)(3072 + g * 128 + e) * 1024 + j0 + half * 16;
;     bf16_t* dq = W0T + (size_t)(4096 + g * 128 + e) * 1024 + j0 + half * 16;
;     uint4 o;
;     o.x = pk2(ap[0], ap[1]); o.y = pk2(ap[2], ap[3]); o.z = pk2(ap[4], ap[5]); o.w = pk2(ap[6], ap[7]); *(uint4*)dp = o;
;     o.x = pk2(ap[8], ap[9]); o.y = pk2(ap[10], ap[11]); o.z = pk2(ap[12], ap[13]); o.w = pk2(ap[14], ap[15]); *(uint4*)(dp + 8) = o;
;     o.x = pk2(aq[0], aq[1]); o.y = pk2(aq[2], aq[3]); o.z = pk2(aq[4], aq[5]); o.w = pk2(aq[6], aq[7]); *(uint4*)dq = o;
;     o.x = pk2(aq[8], aq[9]); o.y = pk2(aq[10], aq[11]); o.z = pk2(aq[12], aq[13]); o.w = pk2(aq[14], aq[15]); *(uint4*)(dq + 8) = o;
	v_mov_b32_e32 v5, v8
	v_mov_b32_e32 v8, v25
	v_mov_b32_e32 v4, v24
	v_pk_mul_f32 v[24:25], v[144:145], v[8:9] op_sel_hi:[0,1]
	v_pk_fma_f32 v[24:25], v[142:143], v[4:5], v[24:25] op_sel_hi:[0,1,1]
	v_mov_b32_e32 v30, v26
	v_mov_b32_e32 v31, v10
	v_pk_fma_f32 v[24:25], v[140:141], v[30:31], v[24:25] op_sel_hi:[0,1,1]
	v_mov_b32_e32 v10, v27
	v_pk_fma_f32 v[24:25], v[138:139], v[10:11], v[24:25] op_sel_hi:[0,1,1]
	v_pk_add_f32 v[102:103], v[0:1], v[24:25]
	v_pk_mul_f32 v[0:1], v[124:125], v[20:21] op_sel_hi:[0,1]
	v_pk_fma_f32 v[0:1], v[122:123], v[170:171], v[0:1] op_sel_hi:[0,1,1]
	v_pk_mul_f32 v[16:17], v[132:133], v[16:17] op_sel_hi:[0,1]
	v_pk_fma_f32 v[0:1], v[126:127], v[184:185], v[0:1] op_sel_hi:[0,1,1]
	v_pk_fma_f32 v[6:7], v[128:129], v[6:7], v[16:17] op_sel_hi:[0,1,1]
	v_pk_fma_f32 v[0:1], v[130:131], v[22:23], v[0:1] op_sel_hi:[0,1,1]
	v_pk_fma_f32 v[6:7], v[134:135], v[186:187], v[6:7] op_sel_hi:[0,1,1]
	v_pk_add_f32 v[0:1], v[34:35], v[0:1]
	v_pk_fma_f32 v[6:7], v[136:137], v[18:19], v[6:7] op_sel_hi:[0,1,1]
	v_pk_add_f32 v[0:1], v[0:1], v[6:7]
	v_pk_mul_f32 v[6:7], v[120:121], v[12:13] op_sel_hi:[0,1]
	v_pk_fma_f32 v[2:3], v[114:115], v[2:3], v[6:7] op_sel_hi:[0,1,1]
	v_pk_fma_f32 v[2:3], v[116:117], v[28:29], v[2:3] op_sel_hi:[0,1,1]
	v_pk_fma_f32 v[2:3], v[118:119], v[14:15], v[2:3] op_sel_hi:[0,1,1]
	v_pk_add_f32 v[0:1], v[0:1], v[2:3]
	v_pk_mul_f32 v[2:3], v[112:113], v[8:9] op_sel_hi:[0,1]
	v_pk_fma_f32 v[2:3], v[110:111], v[4:5], v[2:3] op_sel_hi:[0,1,1]
	v_pk_fma_f32 v[2:3], v[108:109], v[30:31], v[2:3] op_sel_hi:[0,1,1]
	v_pk_fma_f32 v[2:3], v[44:45], v[10:11], v[2:3] op_sel_hi:[0,1,1]
	v_pk_add_f32 v[34:35], v[0:1], v[2:3]
	ds_read_b128 v[28:31], v69 offset:7168
	ds_read_b128 v[24:27], v69 offset:7184
	ds_read_b128 v[20:23], v69 offset:7200
	ds_read_b128 v[16:19], v69 offset:7216
	ds_read_b128 v[12:15], v69 offset:7680
	ds_read_b128 v[8:11], v69 offset:7696
	ds_read_b128 v[4:7], v69 offset:7712
	ds_read_b128 v[0:3], v69 offset:7728
	s_waitcnt lgkmcnt(7)
	v_mov_b32_e32 v170, v28
	s_waitcnt lgkmcnt(3)
	v_mov_b32_e32 v171, v12
	v_mov_b32_e32 v12, v29
	v_pk_mul_f32 v[28:29], v[168:169], v[12:13] op_sel_hi:[0,1]
	v_pk_fma_f32 v[28:29], v[164:165], v[170:171], v[28:29] op_sel_hi:[0,1,1]
	v_mov_b32_e32 v165, v14
	v_mov_b32_e32 v14, v31
	s_waitcnt lgkmcnt(2)
	v_mov_b32_e32 v31, v8
	v_mov_b32_e32 v8, v25
	v_mov_b32_e32 v164, v30
	v_mov_b32_e32 v30, v24
	v_pk_mul_f32 v[24:25], v[160:161], v[8:9] op_sel_hi:[0,1]
	v_pk_fma_f32 v[28:29], v[166:167], v[164:165], v[28:29] op_sel_hi:[0,1,1]
	v_pk_fma_f32 v[24:25], v[158:159], v[30:31], v[24:25] op_sel_hi:[0,1,1]
	v_mov_b32_e32 v166, v26
	v_mov_b32_e32 v167, v10
	v_pk_fma_f32 v[28:29], v[162:163], v[14:15], v[28:29] op_sel_hi:[0,1,1]
	v_pk_fma_f32 v[24:25], v[154:155], v[166:167], v[24:25] op_sel_hi:[0,1,1]
	v_mov_b32_e32 v10, v27
	s_waitcnt lgkmcnt(1)
	v_mov_b32_e32 v27, v4
	v_mov_b32_e32 v4, v21
	v_pk_add_f32 v[28:29], v[104:105], v[28:29]
	v_pk_fma_f32 v[24:25], v[156:157], v[10:11], v[24:25] op_sel_hi:[0,1,1]
	v_mov_b32_e32 v26, v20
	v_pk_mul_f32 v[20:21], v[152:153], v[4:5] op_sel_hi:[0,1]
	v_pk_add_f32 v[24:25], v[28:29], v[24:25]
	v_pk_fma_f32 v[20:21], v[150:151], v[26:27], v[20:21] op_sel_hi:[0,1,1]
	v_mov_b32_e32 v28, v22
	v_mov_b32_e32 v29, v6
	v_pk_fma_f32 v[20:21], v[148:149], v[28:29], v[20:21] op_sel_hi:[0,1,1]
	v_mov_b32_e32 v6, v23
	v_pk_mul_f32 v[12:13], v[124:125], v[12:13] op_sel_hi:[0,1]
	v_pk_fma_f32 v[20:21], v[146:147], v[6:7], v[20:21] op_sel_hi:[0,1,1]
	v_pk_fma_f32 v[12:13], v[122:123], v[170:171], v[12:13] op_sel_hi:[0,1,1]
	v_pk_mul_f32 v[8:9], v[132:133], v[8:9] op_sel_hi:[0,1]
	v_pk_add_f32 v[22:23], v[24:25], v[20:21]
	s_waitcnt lgkmcnt(0)
	v_mov_b32_e32 v21, v0
	v_mov_b32_e32 v0, v17
	v_pk_fma_f32 v[12:13], v[126:127], v[164:165], v[12:13] op_sel_hi:[0,1,1]
	v_pk_fma_f32 v[8:9], v[128:129], v[30:31], v[8:9] op_sel_hi:[0,1,1]
	v_pk_mul_f32 v[4:5], v[120:121], v[4:5] op_sel_hi:[0,1]
	v_mov_b32_e32 v20, v16
	v_pk_mul_f32 v[16:17], v[144:145], v[0:1] op_sel_hi:[0,1]
	v_pk_fma_f32 v[12:13], v[130:131], v[14:15], v[12:13] op_sel_hi:[0,1,1]
	v_pk_fma_f32 v[8:9], v[134:135], v[166:167], v[8:9] op_sel_hi:[0,1,1]
	v_pk_fma_f32 v[4:5], v[114:115], v[26:27], v[4:5] op_sel_hi:[0,1,1]
	v_pk_mul_f32 v[0:1], v[112:113], v[0:1] op_sel_hi:[0,1]
	v_pk_fma_f32 v[24:25], v[142:143], v[20:21], v[16:17] op_sel_hi:[0,1,1]
	v_mov_b32_e32 v16, v18
	v_mov_b32_e32 v17, v2
	v_pk_add_f32 v[12:13], v[106:107], v[12:13]
	v_pk_fma_f32 v[8:9], v[136:137], v[10:11], v[8:9] op_sel_hi:[0,1,1]
	v_pk_fma_f32 v[4:5], v[116:117], v[28:29], v[4:5] op_sel_hi:[0,1,1]
	v_pk_fma_f32 v[0:1], v[110:111], v[20:21], v[0:1] op_sel_hi:[0,1,1]
	v_pk_fma_f32 v[24:25], v[140:141], v[16:17], v[24:25] op_sel_hi:[0,1,1]
	v_mov_b32_e32 v2, v19
	v_pk_add_f32 v[8:9], v[12:13], v[8:9]
	v_pk_fma_f32 v[4:5], v[118:119], v[6:7], v[4:5] op_sel_hi:[0,1,1]
	v_pk_fma_f32 v[0:1], v[108:109], v[16:17], v[0:1] op_sel_hi:[0,1,1]
	v_pk_fma_f32 v[18:19], v[138:139], v[2:3], v[24:25] op_sel_hi:[0,1,1]
	v_pk_add_f32 v[4:5], v[8:9], v[4:5]
	v_pk_fma_f32 v[0:1], v[44:45], v[2:3], v[0:1] op_sel_hi:[0,1,1]
	v_pk_add_f32 v[104:105], v[22:23], v[18:19]
	v_pk_add_f32 v[106:107], v[4:5], v[0:1]
	v_add_u32_e32 v69, 64, v69
	s_cbranch_scc1 .LBB0_162
	v_add_u32_e32 v0, s0, v135
	v_ashrrev_i32_e32 v1, 31, v0
	v_readlane_b32 s6, v230, 19
	v_lshlrev_b64 v[0:1], 11, v[0:1]
	v_readlane_b32 s7, v230, 20
	s_lshl_b32 s20, s8, 1
	v_mov_b32_e32 v81, v45
	v_lshl_add_u64 v[0:1], s[6:7], 0, v[0:1]
	v_lshl_add_u64 v[0:1], v[0:1], 0, s[20:21]
	v_lshl_add_u64 v[4:5], v[0:1], 0, v[80:81]
	v_add_u32_e32 v0, s0, v137
	v_ashrrev_i32_e32 v1, 31, v0
	v_lshlrev_b64 v[0:1], 11, v[0:1]
	v_lshl_add_u64 v[0:1], s[6:7], 0, v[0:1]
	v_lshl_add_u64 v[0:1], v[0:1], 0, s[20:21]
	v_lshl_add_u64 v[6:7], v[0:1], 0, v[80:81]
	v_cvt_pk_bf16_f32 v0, v98, v99
	v_cvt_pk_bf16_f32 v1, v94, v95
	v_cvt_pk_bf16_f32 v2, v90, v91
	v_cvt_pk_bf16_f32 v3, v88, v89
	global_store_dwordx4 v[4:5], v[0:3], off
	s_nop 1
	v_cvt_pk_bf16_f32 v0, v96, v97
	v_cvt_pk_bf16_f32 v1, v92, v93
	v_cvt_pk_bf16_f32 v2, v102, v103
	v_cvt_pk_bf16_f32 v3, v104, v105
	global_store_dwordx4 v[4:5], v[0:3], off offset:16
	s_nop 1
	v_cvt_pk_bf16_f32 v0, v86, v87
	v_cvt_pk_bf16_f32 v1, v40, v41
	v_cvt_pk_bf16_f32 v2, v36, v37
	v_cvt_pk_bf16_f32 v3, v32, v33
	global_store_dwordx4 v[6:7], v[0:3], off
	s_nop 1
	v_cvt_pk_bf16_f32 v0, v42, v43
	v_cvt_pk_bf16_f32 v1, v38, v39
	v_cvt_pk_bf16_f32 v2, v34, v35
	v_cvt_pk_bf16_f32 v3, v106, v107
	global_store_dwordx4 v[6:7], v[0:3], off offset:16
	s_branch .LBB0_83
